# non-temporal (nt) loads of the gate logits in the P3 branch-projection epilogue (read-once data no longer displaces re-used lines in L2), on top of v19
# speedup vs baseline: 1.0066x; 1.0063x over previous
.LBB0_593:
	s_lshl_b32 s5, s25, 4
	v_mov_b32_e32 v130, v156
	s_lshl_b32 s4, s3, 5
	s_add_i32 s5, s5, s24
	s_add_i32 s4, s5, s4
	s_ashr_i32 s5, s4, 31
	v_add_u32_e32 v130, s81, v130
	s_lshl_b64 s[4:5], s[4:5], 16
	v_lshl_add_u32 v130, v130, 3, v159
	s_add_u32 s4, s67, s4
	v_ashrrev_i32_e32 v131, 31, v130
	s_addc_u32 s5, s70, s5
	v_lshlrev_b64 v[130:131], 1, v[130:131]
	v_lshl_add_u64 v[154:155], s[4:5], 0, v[130:131]
	v_add_co_u32_e32 v132, vcc, 0x80000, v154
	s_lshl_b32 s4, s3, 3
	s_nop 0
	v_addc_co_u32_e32 v133, vcc, 0, v155, vcc
	global_load_dwordx4 v[138:141], v[154:155], off nt
	global_load_dwordx4 v[134:137], v[132:133], off nt
	s_add_i32 s4, s4, s24
	s_ashr_i32 s5, s4, 31
	s_lshl_b64 s[4:5], s[4:5], 16
	s_add_u32 s4, s71, s4
	s_addc_u32 s5, s72, s5
	s_cmp_gt_i32 s25, 0
	s_cselect_b64 s[6:7], -1, 0
	s_cmp_lt_i32 s25, 1
	s_cselect_b64 s[48:49], -1, 0
	v_lshl_add_u64 v[152:153], s[4:5], 0, v[130:131]
	s_and_b64 vcc, exec, s[48:49]
	s_cbranch_vccnz .LBB0_596
	global_load_dwordx4 v[130:133], v[152:153], off
	s_branch .LBB0_597

.LBB0_601:
	s_nop 1
	v_add_co_u32_e32 v114, vcc, 0x2000, v154
	s_nop 1
	v_addc_co_u32_e32 v115, vcc, 0, v155, vcc
	v_add_co_u32_e32 v116, vcc, 0x82000, v154
	s_nop 1
	v_addc_co_u32_e32 v117, vcc, 0, v155, vcc
	global_load_dwordx4 v[122:125], v[114:115], off nt
	global_load_dwordx4 v[118:121], v[116:117], off nt
	v_cndmask_b32_e64 v114, 0, 1, s[6:7]
	v_cmp_ne_u32_e64 s[4:5], 1, v114
	s_andn2_b64 vcc, exec, s[6:7]
	s_cbranch_vccnz .LBB0_603
	v_add_co_u32_e32 v114, vcc, 0x2000, v152
	s_nop 1
	v_addc_co_u32_e32 v115, vcc, 0, v153, vcc
	global_load_dwordx4 v[114:117], v[114:115], off
	s_branch .LBB0_604

.LBB0_608:
	s_nop 1
	v_add_co_u32_e32 v98, vcc, 0x4000, v154
	s_nop 1
	v_addc_co_u32_e32 v99, vcc, 0, v155, vcc
	v_add_co_u32_e32 v100, vcc, 0x84000, v154
	s_nop 1
	v_addc_co_u32_e32 v101, vcc, 0, v155, vcc
	global_load_dwordx4 v[106:109], v[98:99], off nt
	global_load_dwordx4 v[102:105], v[100:101], off nt
	s_and_b64 vcc, exec, s[4:5]
	s_cbranch_vccnz .LBB0_610
	v_add_co_u32_e32 v98, vcc, 0x4000, v152
	s_nop 1
	v_addc_co_u32_e32 v99, vcc, 0, v153, vcc
	global_load_dwordx4 v[98:101], v[98:99], off
	s_branch .LBB0_611

.LBB0_615:
	s_nop 1
	v_add_co_u32_e32 v82, vcc, 0x6000, v154
	s_nop 1
	v_addc_co_u32_e32 v83, vcc, 0, v155, vcc
	v_add_co_u32_e32 v84, vcc, 0x86000, v154
	s_nop 1
	v_addc_co_u32_e32 v85, vcc, 0, v155, vcc
	global_load_dwordx4 v[90:93], v[82:83], off nt
	global_load_dwordx4 v[86:89], v[84:85], off nt
	s_and_b64 vcc, exec, s[4:5]
	s_cbranch_vccnz .LBB0_617
	v_add_co_u32_e32 v82, vcc, 0x6000, v152
	s_nop 1
	v_addc_co_u32_e32 v83, vcc, 0, v153, vcc
	global_load_dwordx4 v[82:85], v[82:83], off
	s_branch .LBB0_618

.LBB0_622:
	s_nop 1
	v_add_co_u32_e32 v66, vcc, 0x8000, v154
	s_nop 1
	v_addc_co_u32_e32 v67, vcc, 0, v155, vcc
	v_add_co_u32_e32 v68, vcc, 0x88000, v154
	s_nop 1
	v_addc_co_u32_e32 v69, vcc, 0, v155, vcc
	global_load_dwordx4 v[74:77], v[66:67], off nt
	global_load_dwordx4 v[70:73], v[68:69], off nt
	s_and_b64 vcc, exec, s[4:5]
	s_cbranch_vccnz .LBB0_624
	v_add_co_u32_e32 v66, vcc, 0x8000, v152
	s_nop 1
	v_addc_co_u32_e32 v67, vcc, 0, v153, vcc
	global_load_dwordx4 v[66:69], v[66:67], off
	s_branch .LBB0_625

.LBB0_629:
	s_nop 1
	v_add_co_u32_e32 v50, vcc, 0xa000, v154
	s_nop 1
	v_addc_co_u32_e32 v51, vcc, 0, v155, vcc
	v_add_co_u32_e32 v52, vcc, 0x8a000, v154
	s_nop 1
	v_addc_co_u32_e32 v53, vcc, 0, v155, vcc
	global_load_dwordx4 v[58:61], v[50:51], off nt
	global_load_dwordx4 v[54:57], v[52:53], off nt
	s_and_b64 vcc, exec, s[4:5]
	s_cbranch_vccnz .LBB0_631
	v_add_co_u32_e32 v50, vcc, 0xa000, v152
	s_nop 1
	v_addc_co_u32_e32 v51, vcc, 0, v153, vcc
	global_load_dwordx4 v[50:53], v[50:51], off
	s_branch .LBB0_632

.LBB0_636:
	s_nop 1
	v_add_co_u32_e32 v34, vcc, 0xc000, v154
	s_nop 1
	v_addc_co_u32_e32 v35, vcc, 0, v155, vcc
	v_add_co_u32_e32 v36, vcc, 0x8c000, v154
	s_nop 1
	v_addc_co_u32_e32 v37, vcc, 0, v155, vcc
	global_load_dwordx4 v[42:45], v[34:35], off nt
	global_load_dwordx4 v[38:41], v[36:37], off nt
	s_and_b64 vcc, exec, s[4:5]
	s_cbranch_vccnz .LBB0_638
	v_add_co_u32_e32 v34, vcc, 0xc000, v152
	s_nop 1
	v_addc_co_u32_e32 v35, vcc, 0, v153, vcc
	global_load_dwordx4 v[34:37], v[34:35], off
	s_branch .LBB0_639

.LBB0_643:
	s_nop 1
	v_add_co_u32_e32 v18, vcc, 0xe000, v154
	s_nop 1
	v_addc_co_u32_e32 v19, vcc, 0, v155, vcc
	v_add_co_u32_e32 v20, vcc, 0x8e000, v154
	s_nop 1
	v_addc_co_u32_e32 v21, vcc, 0, v155, vcc
	global_load_dwordx4 v[26:29], v[18:19], off nt
	global_load_dwordx4 v[22:25], v[20:21], off nt
	s_and_b64 vcc, exec, s[4:5]
	s_cbranch_vccnz .LBB0_645
	v_add_co_u32_e32 v18, vcc, 0xe000, v152
	s_nop 1
	v_addc_co_u32_e32 v19, vcc, 0, v153, vcc
	global_load_dwordx4 v[18:21], v[18:19], off
	s_branch .LBB0_646
